# wait states between v_cmp and the vcc branch in the four counter spin loops (stale-VCCZ hazard found with a failing variant)
# baseline (speedup 1.0000x reference)
.Lcmb_poll:
	global_load_dword v19, v1, s[4:5] sc1
	s_waitcnt vmcnt(0)
	v_cmp_le_u32_e32 vcc, v18, v19
	s_nop 4
	s_cbranch_vccnz .Lcmb_go
	s_sleep 2
	s_branch .Lcmb_poll

.Lhf_loop:
	global_load_dword v6, v3, s[6:7] sc1
	global_load_dword v7, v4, s[6:7] sc1
	global_load_dword v8, v5, s[6:7] sc1
	global_load_dword v11, v10, s[6:7] sc1
	s_waitcnt vmcnt(0)
	v_min3_u32 v6, v6, v7, v8
	v_cmp_le_u32_e32 vcc, v2, v6
	s_nop 4
	s_cbranch_vccz .Lhf_slp
	v_cmp_le_u32_e32 vcc, v9, v11
	s_nop 1
	s_andn2_b64 s[0:1], exec, vcc
	s_cbranch_scc0 .Lhf_rel

.Lytf_poll:
	global_load_dword v5, v1, s[6:7] sc1
	s_waitcnt vmcnt(0)
	v_cmp_le_u32_e32 vcc, s3, v5
	s_nop 4
	s_cbranch_vccnz .Lytf_go
	s_sleep 2
	s_branch .Lytf_poll

.Lfc_poll:
	global_load_dword v3, v17, s[8:9] sc1
	s_waitcnt vmcnt(0)
	v_cmp_le_u32_e32 vcc, v2, v3
	s_nop 4
	s_cbranch_vccnz .Lfc_go
	s_sleep 2
	s_branch .Lfc_poll
